# FFN adaLN phase: modulation-vector loads hoisted ahead of the row loads (4 serialized L2 round trips per row removed)
# speedup vs baseline: 1.0135x; 1.0135x over previous
.LBB0_777:
	s_waitcnt vmcnt(3)
	v_pk_mul_f32 v[42:43], v[32:33], v[32:33]
	v_pk_mul_f32 v[44:45], v[30:31], v[30:31]
	s_waitcnt vmcnt(2)
	v_pk_mul_f32 v[38:39], v[28:29], v[28:29]
	v_pk_mul_f32 v[40:41], v[26:27], v[26:27]
	v_pk_mov_b32 v[46:47], v[44:45], v[42:43] op_sel:[1,0]
	v_mov_b32_e32 v45, v43
	v_pk_add_f32 v[42:43], v[46:47], v[44:45]
	v_pk_mov_b32 v[44:45], v[40:41], v[38:39] op_sel:[1,0]
	v_mov_b32_e32 v41, v39
	s_waitcnt vmcnt(1)
	v_mul_f32_e32 v0, v22, v22
	v_pk_add_f32 v[38:39], v[44:45], v[40:41]
	v_pk_fma_f32 v[40:41], v[22:23], v[22:23], v[0:1] op_sel_hi:[1,1,0]
	v_mul_f32_e32 v0, v24, v24
	v_pk_add_f32 v[42:43], v[42:43], v[42:43] op_sel_hi:[0,1]
	v_pk_add_f32 v[38:39], v[38:39], v[38:39] op_sel_hi:[0,1]
	v_pk_fma_f32 v[44:45], v[24:25], v[24:25], v[0:1] op_sel_hi:[1,1,0]
	s_waitcnt vmcnt(0)
	v_mul_f32_e32 v40, v18, v18
	v_mul_f32_e32 v44, v19, v19
	v_mul_f32_e32 v42, v20, v20
	v_mul_f32_e32 v38, v21, v21
	v_pk_add_f32 v[40:41], v[40:41], v[44:45]
	v_pk_add_f32 v[38:39], v[42:43], v[38:39]
	s_min_i32 s2, s24, 0x8000
	v_pk_add_f32 v[38:39], v[40:41], v[38:39]
	s_ashr_i32 s2, s2, 11
	v_add_f32_e32 v0, v38, v39
	ds_bpermute_b32 v38, v35, v0
	s_mul_hi_i32 s3, s2, 0x9000
	s_mul_i32 s2, s2, 0x9000
	s_add_u32 s4, s28, s2
	s_addc_u32 s5, s29, s3
	s_waitcnt lgkmcnt(0)
	v_add_f32_e32 v0, v0, v38
	ds_bpermute_b32 v38, v48, v0
	s_add_u32 s96, s4, 0x1000
	s_addc_u32 s97, s5, 0
	v_lshlrev_b32_e32 v46, 2, v34
	s_add_i32 s24, s24, s10
	s_waitcnt lgkmcnt(0)
	v_add_f32_e32 v0, v0, v38
	ds_bpermute_b32 v38, v49, v0
	s_cmp_lt_i32 s24, s20
	s_waitcnt lgkmcnt(0)
	v_add_f32_e32 v0, v0, v38
	ds_bpermute_b32 v38, v50, v0
	s_waitcnt lgkmcnt(0)
	v_add_f32_e32 v0, v0, v38
	ds_bpermute_b32 v38, v51, v0
	s_waitcnt lgkmcnt(0)
	v_add_f32_e32 v0, v0, v38
	ds_bpermute_b32 v38, v52, v0
	s_waitcnt lgkmcnt(0)
	v_add_f32_e32 v0, v0, v38
	v_fmamk_f32 v0, v0, 0x3a800000, v240
	v_cmp_gt_f32_e32 vcc, s77, v0
	v_mul_f32_e32 v38, 0x4f800000, v0
	s_nop 0
	v_cndmask_b32_e32 v0, v0, v38, vcc
	v_sqrt_f32_e32 v38, v0
	s_nop 0
	v_add_u32_e32 v39, -1, v38
	v_fma_f32 v40, -v39, v38, v0
	v_cmp_ge_f32_e64 s[2:3], 0, v40
	v_add_u32_e32 v40, 1, v38
	s_nop 0
	v_cndmask_b32_e64 v39, v38, v39, s[2:3]
	v_fma_f32 v38, -v40, v38, v0
	v_cmp_lt_f32_e64 s[2:3], 0, v38
	s_nop 1
	v_cndmask_b32_e64 v38, v39, v40, s[2:3]
	v_mul_f32_e32 v39, 0x37800000, v38
	v_cndmask_b32_e32 v38, v38, v39, vcc
	v_cmp_class_f32_e32 vcc, v0, v241
	s_nop 1
	v_cndmask_b32_e32 v0, v38, v0, vcc
	v_div_scale_f32 v38, s[2:3], v0, v0, 1.0
	v_rcp_f32_e32 v39, v38
	s_nop 0
	v_fma_f32 v40, -v38, v39, 1.0
	v_fmac_f32_e32 v39, v40, v39
	v_div_scale_f32 v40, vcc, 1.0, v0, 1.0
	v_mul_f32_e32 v41, v40, v39
	v_fma_f32 v42, -v38, v41, v40
	v_fmac_f32_e32 v41, v42, v39
	v_fma_f32 v38, -v38, v41, v40
	v_div_fmas_f32 v38, v38, v39, v41
	v_div_fixup_f32 v0, v38, v0, 1.0
	v_pk_mul_f32 v[32:33], v[32:33], v[0:1] op_sel_hi:[1,0]
	v_pk_mul_f32 v[30:31], v[30:31], v[0:1] op_sel_hi:[1,0]
	v_pk_mul_f32 v[32:33], v[4:5], v[32:33]
	v_pk_mul_f32 v[30:31], v[2:3], v[30:31]
	v_pk_mul_f32 v[28:29], v[28:29], v[0:1] op_sel_hi:[1,0]
	v_pk_mul_f32 v[26:27], v[26:27], v[0:1] op_sel_hi:[1,0]
	v_pk_mul_f32 v[28:29], v[8:9], v[28:29]
	v_pk_mul_f32 v[26:27], v[6:7], v[26:27]
	v_pk_mul_f32 v[24:25], v[24:25], v[0:1] op_sel_hi:[1,0]
	v_pk_mul_f32 v[22:23], v[22:23], v[0:1] op_sel_hi:[1,0]
	v_pk_mul_f32 v[24:25], v[12:13], v[24:25]
	v_pk_mul_f32 v[22:23], v[10:11], v[22:23]
	v_pk_mul_f32 v[20:21], v[20:21], v[0:1] op_sel_hi:[1,0]
	v_pk_mul_f32 v[18:19], v[18:19], v[0:1] op_sel_hi:[1,0]
	v_pk_mul_f32 v[20:21], v[16:17], v[20:21]
	v_pk_mul_f32 v[18:19], v[14:15], v[18:19]
	v_pk_add_f32 v[118:119], v[118:119], 1.0 op_sel_hi:[1,0]
	v_pk_add_f32 v[116:117], v[116:117], 1.0 op_sel_hi:[1,0]
	v_pk_add_f32 v[122:123], v[122:123], 1.0 op_sel_hi:[1,0]
	v_pk_add_f32 v[120:121], v[120:121], 1.0 op_sel_hi:[1,0]
	v_pk_fma_f32 v[32:33], v[118:119], v[32:33], v[102:103]
	v_pk_fma_f32 v[30:31], v[116:117], v[30:31], v[100:101]
	v_pk_add_f32 v[126:127], v[126:127], 1.0 op_sel_hi:[1,0]
	v_pk_add_f32 v[124:125], v[124:125], 1.0 op_sel_hi:[1,0]
	v_cvt_pk_bf16_f32 v30, v30, v31
	v_cvt_pk_bf16_f32 v31, v32, v33
	global_store_dwordx2 v[36:37], v[30:31], off
	v_pk_fma_f32 v[28:29], v[122:123], v[28:29], v[106:107]
	v_pk_fma_f32 v[26:27], v[120:121], v[26:27], v[104:105]
	v_pk_add_f32 v[130:131], v[130:131], 1.0 op_sel_hi:[1,0]
	v_pk_add_f32 v[128:129], v[128:129], 1.0 op_sel_hi:[1,0]
	v_cvt_pk_bf16_f32 v26, v26, v27
	v_cvt_pk_bf16_f32 v27, v28, v29
	global_store_dwordx2 v[36:37], v[26:27], off offset:512
	v_pk_fma_f32 v[24:25], v[126:127], v[24:25], v[110:111]
	v_pk_fma_f32 v[22:23], v[124:125], v[22:23], v[108:109]
	s_nop 0
	v_cvt_pk_bf16_f32 v22, v22, v23
	v_cvt_pk_bf16_f32 v23, v24, v25
	global_store_dwordx2 v[36:37], v[22:23], off offset:1024
	v_pk_fma_f32 v[20:21], v[130:131], v[20:21], v[114:115]
	v_pk_fma_f32 v[18:19], v[128:129], v[18:19], v[112:113]
	s_nop 0
	v_cvt_pk_bf16_f32 v18, v18, v19
	v_cvt_pk_bf16_f32 v19, v20, v21
	global_store_dwordx2 v[36:37], v[18:19], off offset:1536
	v_lshl_add_u64 v[36:37], v[36:37], 0, s[56:57]
	s_cbranch_scc0 .LBB0_784
.LBB0_778:
	s_min_i32 s98, s24, 0x8000
	s_ashr_i32 s98, s98, 11
	s_mul_hi_i32 s99, s98, 0x9000
	s_mul_i32 s98, s98, 0x9000
	s_add_u32 s98, s28, s98
	s_addc_u32 s99, s29, s99
	s_add_u32 s100, s98, 0x1000
	s_addc_u32 s101, s99, 0
	v_lshlrev_b32_e32 v132, 2, v34
	global_load_dwordx4 v[100:103], v132, s[98:99]
	global_load_dwordx4 v[104:107], v132, s[98:99] offset:1024
	global_load_dwordx4 v[108:111], v132, s[98:99] offset:2048
	global_load_dwordx4 v[112:115], v132, s[98:99] offset:3072
	global_load_dwordx4 v[116:119], v132, s[100:101]
	global_load_dwordx4 v[120:123], v132, s[100:101] offset:1024
	global_load_dwordx4 v[124:127], v132, s[100:101] offset:2048
	global_load_dwordx4 v[128:131], v132, s[100:101] offset:3072
	s_add_i32 s9, s24, 0xffff8000
	s_cmpk_gt_i32 s24, 0x7fff
	s_cselect_b64 s[2:3], -1, 0
	s_and_b64 s[4:5], s[2:3], exec
	s_cselect_b32 s26, s9, s24
	s_cselect_b32 s5, s23, s13
	s_cselect_b32 s4, s22, s12
	s_ashr_i32 s27, s26, 31
	s_lshl_b64 s[26:27], s[26:27], 10
	v_mov_b32_e32 v39, s27
	v_or_b32_e32 v38, s26, v34
	s_mov_b64 s[26:27], -1
	s_and_b64 vcc, exec, s[72:73]
	s_cbranch_vccz .LBB0_781
	v_lshl_add_u64 v[18:19], v[38:39], 1, s[4:5]
	global_load_dwordx2 v[20:21], v[18:19], off
	global_load_dwordx2 v[22:23], v[18:19], off offset:512
	global_load_dwordx2 v[24:25], v[18:19], off offset:1024
	global_load_dwordx2 v[40:41], v[18:19], off offset:1536
	s_waitcnt vmcnt(3)
	v_cvt_f32_f16_e32 v30, v20
	v_cvt_f32_f16_sdwa v31, v20 dst_sel:DWORD dst_unused:UNUSED_PAD src0_sel:WORD_1
	v_cvt_f32_f16_e32 v32, v21
	v_cvt_f32_f16_sdwa v33, v21 dst_sel:DWORD dst_unused:UNUSED_PAD src0_sel:WORD_1
	s_waitcnt vmcnt(2)
	v_cvt_f32_f16_e32 v26, v22
	v_cvt_f32_f16_sdwa v27, v22 dst_sel:DWORD dst_unused:UNUSED_PAD src0_sel:WORD_1
	v_cvt_f32_f16_e32 v28, v23
	v_cvt_f32_f16_sdwa v29, v23 dst_sel:DWORD dst_unused:UNUSED_PAD src0_sel:WORD_1
	s_waitcnt vmcnt(1)
	v_cvt_f32_f16_e32 v22, v24
	v_cvt_f32_f16_sdwa v23, v24 dst_sel:DWORD dst_unused:UNUSED_PAD src0_sel:WORD_1
	v_cvt_f32_f16_e32 v24, v25
	v_cvt_f32_f16_sdwa v25, v25 dst_sel:DWORD dst_unused:UNUSED_PAD src0_sel:WORD_1
	s_waitcnt vmcnt(0)
	v_cvt_f32_f16_e32 v18, v40
	v_cvt_f32_f16_sdwa v19, v40 dst_sel:DWORD dst_unused:UNUSED_PAD src0_sel:WORD_1
	v_cvt_f32_f16_e32 v20, v41
	v_cvt_f32_f16_sdwa v21, v41 dst_sel:DWORD dst_unused:UNUSED_PAD src0_sel:WORD_1
	s_cbranch_execz .LBB0_782

	.amdhsa_kernel _Z14fwd_megakernel4Args
		.amdhsa_group_segment_fixed_size 0
		.amdhsa_private_segment_fixed_size 0
		.amdhsa_kernarg_size 560
		.amdhsa_user_sgpr_count 2
		.amdhsa_user_sgpr_dispatch_ptr 0
		.amdhsa_user_sgpr_queue_ptr 0
		.amdhsa_user_sgpr_kernarg_segment_ptr 1
		.amdhsa_user_sgpr_dispatch_id 0
		.amdhsa_user_sgpr_kernarg_preload_length 0
		.amdhsa_user_sgpr_kernarg_preload_offset 0
		.amdhsa_user_sgpr_private_segment_size 0
		.amdhsa_uses_dynamic_stack 0
		.amdhsa_enable_private_segment 0
		.amdhsa_system_sgpr_workgroup_id_x 1
		.amdhsa_system_sgpr_workgroup_id_y 0
		.amdhsa_system_sgpr_workgroup_id_z 0
		.amdhsa_system_sgpr_workgroup_info 0
		.amdhsa_system_vgpr_workitem_id 2
		.amdhsa_next_free_vgpr 256
		.amdhsa_next_free_sgpr 102
		.amdhsa_accum_offset 256
		.amdhsa_reserve_vcc 1
		.amdhsa_float_round_mode_32 0
		.amdhsa_float_round_mode_16_64 0
		.amdhsa_float_denorm_mode_32 3
		.amdhsa_float_denorm_mode_16_64 3
		.amdhsa_dx10_clamp 1
		.amdhsa_ieee_mode 1
		.amdhsa_fp16_overflow 0
		.amdhsa_tg_split 0
		.amdhsa_exception_fp_ieee_invalid_op 0
		.amdhsa_exception_fp_denorm_src 0
		.amdhsa_exception_fp_ieee_div_zero 0
		.amdhsa_exception_fp_ieee_overflow 0
		.amdhsa_exception_fp_ieee_underflow 0
		.amdhsa_exception_fp_ieee_inexact 0
		.amdhsa_exception_int_div_zero 0
	.end_amdhsa_kernel

amdhsa.kernels:
  - .agpr_count:     0
    .args:
      - .offset:         0
        .size:           304
        .value_kind:     by_value
      - .offset:         304
        .size:           4
        .value_kind:     hidden_block_count_x
      - .offset:         308
        .size:           4
        .value_kind:     hidden_block_count_y
      - .offset:         312
        .size:           4
        .value_kind:     hidden_block_count_z
      - .offset:         316
        .size:           2
        .value_kind:     hidden_group_size_x
      - .offset:         318
        .size:           2
        .value_kind:     hidden_group_size_y
      - .offset:         320
        .size:           2
        .value_kind:     hidden_group_size_z
      - .offset:         322
        .size:           2
        .value_kind:     hidden_remainder_x
      - .offset:         324
        .size:           2
        .value_kind:     hidden_remainder_y
      - .offset:         326
        .size:           2
        .value_kind:     hidden_remainder_z
      - .offset:         344
        .size:           8
        .value_kind:     hidden_global_offset_x
      - .offset:         352
        .size:           8
        .value_kind:     hidden_global_offset_y
      - .offset:         360
        .size:           8
        .value_kind:     hidden_global_offset_z
      - .offset:         368
        .size:           2
        .value_kind:     hidden_grid_dims
      - .offset:         392
        .size:           8
        .value_kind:     hidden_multigrid_sync_arg
      - .offset:         424
        .size:           4
        .value_kind:     hidden_dynamic_lds_size
    .group_segment_fixed_size: 0
    .kernarg_segment_align: 8
    .kernarg_segment_size: 560
    .language:       OpenCL C
    .language_version:
      - 2
      - 0
    .max_flat_workgroup_size: 512
    .name:           _Z14fwd_megakernel4Args
    .private_segment_fixed_size: 0
    .sgpr_count:     108
    .sgpr_spill_count: 65
    .symbol:         _Z14fwd_megakernel4Args.kd
    .uniform_work_group_size: 1
    .uses_dynamic_stack: false
    .vgpr_count:     256
    .vgpr_spill_count: 0
    .wavefront_size: 64
